# attention loops: output-accumulator rescale by plain f32 multiplies instead of packed v_pk_mul_f32 next to the MFMAs
# speedup vs baseline: 1.0018x; 1.0018x over previous
; __device__ __forceinline__ void nsa_wave(CArgs* Ap, int l, int b, int g, int tq0, const LAS float* lut, LAS float* imp, int lane) {
;     ...
;             for (int hs = 0; hs < 2 * ns; ++hs) {
;                 const int s = hs >> 1, hh = hs & 1;
;                 const int j = __builtin_amdgcn_readlane(selreg, s);
;                 const bool more = hs + 1 < 2 * ns; const int s1 = (hs + 1) >> 1, h1 = (hs + 1) & 1;
;                 const int jn = more ? __builtin_amdgcn_readlane(selreg, s1) : 0;
;                 f32x4 acc[2];
;                 acc[0] = (f32x4){0.f, 0.f, 0.f, 0.f}; acc[1] = (f32x4){0.f, 0.f, 0.f, 0.f};
;                 qk_acch8(acc, kh, q8);
;                 if (more) load_kh8(kh, Ks8 + (size_t)jn * 4096, h1, lane);
;                 if (__all(t - (j * 64 + 32 * hh + 31) >= 1023)) softmax_half_far(acc, lutg, st, Od);
;                 else { bf16x8 pB; softmax_half<1>(acc, j * 64 + 32 * hh, true, t, g4, lutg, st, Od, pB); }
;                 pv_acch8(Od, vh, p_to_fp8(acc));
;                 if (more) load_vh8(vh, Vs8 + (size_t)jn * 4096, h1, lane);
.Lssl_join:
	v_sub_f32_e32 v24, v49, v144
	v_cvt_pk_fp8_f32 v26, v50, v51
	v_mul_f32_e32 v24, 0x3fb8aa3b, v24
	v_cvt_pk_fp8_f32 v27, v54, v55
	v_exp_f32_e32 v24, v24
	v_cvt_pk_fp8_f32 v26, v52, v53 op_sel:[0,0,1]
	v_cvt_pk_fp8_f32 v27, v56, v57 op_sel:[0,0,1]
	v_mul_f32_e32 v23, v24, v23
	v_mul_f32_e32 v22, v24, v22
	v_mul_f32_e32 v21, v24, v21
	v_mul_f32_e32 v20, v24, v20
	v_mul_f32_e32 v19, v24, v19
	v_mul_f32_e32 v18, v24, v18
	v_mul_f32_e32 v17, v24, v17
	v_mul_f32_e32 v16, v24, v16
	v_mul_f32_e32 v15, v24, v15
	v_mul_f32_e32 v14, v24, v14
	v_mul_f32_e32 v13, v24, v13
	v_mul_f32_e32 v12, v24, v12
	v_mul_f32_e32 v11, v24, v11
	v_mul_f32_e32 v10, v24, v10
	v_mul_f32_e32 v9, v24, v9
	v_mul_f32_e32 v8, v24, v8
	s_waitcnt vmcnt(1)
	v_mfma_f32_16x16x32_fp8_fp8 v[20:23], v[40:41], v[26:27], v[20:23]
	s_and_b64 vcc, exec, s[46:47]
	s_nop 0
	v_mfma_f32_16x16x32_fp8_fp8 v[16:19], v[42:43], v[26:27], v[16:19]
	s_waitcnt vmcnt(0)
	v_mfma_f32_16x16x32_fp8_fp8 v[12:15], v[44:45], v[26:27], v[12:15]
	s_nop 0
	v_mfma_f32_16x16x32_fp8_fp8 v[8:11], v[46:47], v[26:27], v[8:11]
	s_cbranch_vccnz .LBB0_1256
	s_add_u32 s46, s0, s62
	s_addc_u32 s47, s1, s63
	v_lshl_or_b32 v25, s66, 11, v84
	global_load_dwordx4 v[40:43], v25, s[46:47]
	global_load_dwordx4 v[44:47], v25, s[46:47] offset:1024

; __device__ __forceinline__ void nsa_wave(CArgs* Ap, int l, int b, int g, int tq0, const LAS float* lut, LAS float* imp, int lane) {
;     ...
;         for (int hs = h0; hs < nh; ++hs) {
;             const int s = hs >> 1, hh = hs & 1;
;             const int jm = __shfl(selreg, 16 * qi + s);
;             f32x4 acc[2];
;             acc[0] = (f32x4){0.f, 0.f, 0.f, 0.f}; acc[1] = (f32x4){0.f, 0.f, 0.f, 0.f};
; #pragma unroll
;             for (int q2 = 0; q2 < 4; ++q2) { long qm[2]; qm[0] = (qi == q2) ? q8[0] : 0l; qm[1] = (qi == q2) ? q8[1] : 0l; qk_acch8(acc, kq[q2], qm); }
;             const bool more = hs + 1 < nh; const int s1 = (hs + 1) >> 1, h1 = (hs + 1) & 1;
;             int jn[4];
; #pragma unroll
;             for (int q2 = 0; q2 < 4; ++q2) { int j = more ? __builtin_amdgcn_readlane(selreg, 16 * q2 + s1) : 0; jn[q2] = j < 0 ? 0 : j; }
;             if (more) {
; #pragma unroll
;                 for (int q2 = 0; q2 < 4; ++q2) load_kh8(kq[q2], Ks8 + (size_t)jn[q2] * 4096, h1, lane); }
;             if (__all(jm >= 0 && t - (jm * 64 + 32 * hh + 31) >= 1023)) softmax_half_far(acc, lutg, st, Od);
;             else { bf16x8 pB; softmax_half<1>(acc, (jm < 0 ? 0 : jm) * 64 + 32 * hh, jm >= 0, t, g4, lutg, st, Od, pB); }
;             const long p8 = p_to_fp8(acc);
; #pragma unroll
;             for (int q2 = 0; q2 < 4; ++q2) { const long pm = (qi == q2) ? p8 : 0l; pv_acch8(Od, vq[q2], pm); }
;             if (more) {
; #pragma unroll
;                 for (int q2 = 0; q2 < 4; ++q2) load_vh8(vq[q2], Vs8 + (size_t)jn[q2] * 4096, h1, lane); }
.Lsla_join:
	v_sub_f32_e32 v24, v144, v213
	v_cvt_pk_fp8_f32 v31, v216, v217
	v_mul_f32_e32 v24, 0x3fb8aa3b, v24
	v_cvt_pk_fp8_f32 v144, v220, v221
	v_exp_f32_e32 v24, v24
	v_cvt_pk_fp8_f32 v31, v218, v219 op_sel:[0,0,1]
	v_cvt_pk_fp8_f32 v144, v222, v223 op_sel:[0,0,1]
	v_mul_f32_e32 v23, v24, v23
	v_mul_f32_e32 v22, v24, v22
	v_mul_f32_e32 v21, v24, v21
	v_mul_f32_e32 v20, v24, v20
	v_cndmask_b32_e64 v27, 0, v144, s[6:7]
	v_cndmask_b32_e64 v26, 0, v31, s[6:7]
	v_mul_f32_e32 v19, v24, v19
	v_mul_f32_e32 v18, v24, v18
	v_mul_f32_e32 v17, v24, v17
	v_mul_f32_e32 v16, v24, v16
	v_mul_f32_e32 v15, v24, v15
	v_mul_f32_e32 v14, v24, v14
	v_mul_f32_e32 v13, v24, v13
	v_mul_f32_e32 v12, v24, v12
	v_mul_f32_e32 v11, v24, v11
	v_mul_f32_e32 v10, v24, v10
	v_mul_f32_e32 v9, v24, v9
	v_mul_f32_e32 v8, v24, v8
	s_waitcnt vmcnt(31)
	s_nop 0
	v_mfma_f32_16x16x32_fp8_fp8 v[20:23], v[40:41], v[26:27], v[20:23]
	v_mfma_f32_16x16x32_fp8_fp8 v[16:19], v[42:43], v[26:27], v[16:19]
	s_waitcnt vmcnt(30)
	v_mfma_f32_16x16x32_fp8_fp8 v[12:15], v[44:45], v[26:27], v[12:15]
	v_mfma_f32_16x16x32_fp8_fp8 v[8:11], v[46:47], v[26:27], v[8:11]
	v_cndmask_b32_e64 v27, 0, v144, s[8:9]
	v_cndmask_b32_e64 v26, 0, v31, s[8:9]
	s_waitcnt vmcnt(29)
	s_nop 0
	v_mfma_f32_16x16x32_fp8_fp8 v[20:23], v[56:57], v[26:27], v[20:23]
	v_mfma_f32_16x16x32_fp8_fp8 v[16:19], v[58:59], v[26:27], v[16:19]
	s_waitcnt vmcnt(28)
	v_mfma_f32_16x16x32_fp8_fp8 v[12:15], v[60:61], v[26:27], v[12:15]
	v_mfma_f32_16x16x32_fp8_fp8 v[8:11], v[62:63], v[26:27], v[8:11]
	v_cndmask_b32_e64 v27, 0, v144, s[10:11]
	v_cndmask_b32_e64 v26, 0, v31, s[10:11]
	s_waitcnt vmcnt(27)
	s_nop 0
	v_mfma_f32_16x16x32_fp8_fp8 v[20:23], v[74:75], v[26:27], v[20:23]
	v_mfma_f32_16x16x32_fp8_fp8 v[16:19], v[76:77], v[26:27], v[16:19]
	s_waitcnt vmcnt(26)
	v_mfma_f32_16x16x32_fp8_fp8 v[12:15], v[78:79], v[26:27], v[12:15]
	v_mfma_f32_16x16x32_fp8_fp8 v[8:11], v[80:81], v[26:27], v[8:11]
	v_cndmask_b32_e64 v27, 0, v144, s[12:13]
	v_cndmask_b32_e64 v26, 0, v31, s[12:13]
	s_waitcnt vmcnt(25)
	s_nop 0
	v_mfma_f32_16x16x32_fp8_fp8 v[20:23], v[106:107], v[26:27], v[20:23]
	v_mfma_f32_16x16x32_fp8_fp8 v[16:19], v[108:109], v[26:27], v[16:19]
	s_waitcnt vmcnt(24)
	v_mfma_f32_16x16x32_fp8_fp8 v[12:15], v[122:123], v[26:27], v[12:15]
	v_mfma_f32_16x16x32_fp8_fp8 v[8:11], v[124:125], v[26:27], v[8:11]
	s_add_u32 s48, s0, s26
	s_addc_u32 s49, s1, s27
	global_load_dwordx4 v[40:43], v84, s[48:49]
	global_load_dwordx4 v[44:47], v84, s[48:49] offset:1024
	s_add_u32 s48, s0, s28
	s_addc_u32 s49, s1, s29
	global_load_dwordx4 v[56:59], v84, s[48:49]
	global_load_dwordx4 v[60:63], v84, s[48:49] offset:1024
	s_add_u32 s48, s0, s30
	s_addc_u32 s49, s1, s31
	global_load_dwordx4 v[74:77], v84, s[48:49]
	global_load_dwordx4 v[78:81], v84, s[48:49] offset:1024
	s_add_u32 s48, s0, s34
	s_addc_u32 s49, s1, s35
	global_load_dwordx4 v[106:109], v84, s[48:49]
	global_load_dwordx4 v[122:125], v84, s[48:49] offset:1024
	v_fmac_f32_e32 v215, v212, v24
	s_add_i32 s24, s24, 32
	s_nop 0
	v_mov_b32_e32 v212, v215
	v_mov_b32_e32 v144, v213
	s_waitcnt vmcnt(31)
	v_mfma_f32_16x16x32_fp8_fp8 v[24:27], v[184:185], v[82:83], 0
	v_mov_b32_e32 v214, v165
	s_nop 0
	s_waitcnt vmcnt(30)
	v_mfma_f32_16x16x32_fp8_fp8 v[28:31], v[188:189], v[82:83], 0
	s_nop 0
	s_nop 0
	v_mfma_f32_16x16x32_fp8_fp8 v[24:27], v[186:187], v[104:105], v[24:27]
	v_mfma_f32_16x16x32_fp8_fp8 v[28:31], v[190:191], v[104:105], v[28:31]
	s_waitcnt vmcnt(29)
	v_mfma_f32_16x16x32_fp8_fp8 v[24:27], v[192:193], v[98:99], v[24:27]
	s_waitcnt vmcnt(28)
	v_mfma_f32_16x16x32_fp8_fp8 v[28:31], v[196:197], v[98:99], v[28:31]
	v_mfma_f32_16x16x32_fp8_fp8 v[24:27], v[194:195], v[110:111], v[24:27]
	v_mfma_f32_16x16x32_fp8_fp8 v[28:31], v[198:199], v[110:111], v[28:31]
	s_waitcnt vmcnt(27)
	v_mfma_f32_16x16x32_fp8_fp8 v[24:27], v[230:231], v[100:101], v[24:27]
	s_waitcnt vmcnt(26)
	v_mfma_f32_16x16x32_fp8_fp8 v[28:31], v[234:235], v[100:101], v[28:31]
	v_mfma_f32_16x16x32_fp8_fp8 v[24:27], v[232:233], v[120:121], v[24:27]
	v_mfma_f32_16x16x32_fp8_fp8 v[28:31], v[236:237], v[120:121], v[28:31]
	s_waitcnt vmcnt(25)
	v_mfma_f32_16x16x32_fp8_fp8 v[24:27], v[238:239], v[102:103], v[24:27]
	s_waitcnt vmcnt(24)
	v_mfma_f32_16x16x32_fp8_fp8 v[28:31], v[242:243], v[102:103], v[28:31]
	v_mfma_f32_16x16x32_fp8_fp8 v[24:27], v[240:241], v[126:127], v[24:27]
	v_mfma_f32_16x16x32_fp8_fp8 v[28:31], v[244:245], v[126:127], v[28:31]
	s_add_u32 s48, s96, s26
	s_addc_u32 s49, s97, s27
	global_load_dwordx4 v[184:187], v229, s[48:49]
	global_load_dwordx4 v[188:191], v229, s[48:49] offset:1024
	s_add_u32 s48, s96, s28
	s_addc_u32 s49, s97, s29
	global_load_dwordx4 v[192:195], v229, s[48:49]
	global_load_dwordx4 v[196:199], v229, s[48:49] offset:1024
	s_add_u32 s48, s96, s30
	s_addc_u32 s49, s97, s31
	global_load_dwordx4 v[230:233], v229, s[48:49]
	global_load_dwordx4 v[234:237], v229, s[48:49] offset:1024
	s_add_u32 s48, s96, s34
	s_addc_u32 s49, s97, s35
	global_load_dwordx4 v[238:241], v229, s[48:49]
	global_load_dwordx4 v[242:245], v229, s[48:49] offset:1024

; __device__ __forceinline__ void nsa_wave(CArgs* Ap, int l, int b, int g, int tq0, const LAS float* lut, LAS float* imp, int lane) {
;     ...
;         for (int hs = h0; hs < nh; ++hs) {
;             const int s = hs >> 1, hh = hs & 1;
;             const int jm = __shfl(selreg, 16 * qi + s);
;             f32x4 acc[2];
;             acc[0] = (f32x4){0.f, 0.f, 0.f, 0.f}; acc[1] = (f32x4){0.f, 0.f, 0.f, 0.f};
; #pragma unroll
;             for (int q2 = 0; q2 < 4; ++q2) { long qm[2]; qm[0] = (qi == q2) ? q8[0] : 0l; qm[1] = (qi == q2) ? q8[1] : 0l; qk_acch8(acc, kq[q2], qm); }
;             const bool more = hs + 1 < nh; const int s1 = (hs + 1) >> 1, h1 = (hs + 1) & 1;
;             int jn[4];
; #pragma unroll
;             for (int q2 = 0; q2 < 4; ++q2) { int j = more ? __builtin_amdgcn_readlane(selreg, 16 * q2 + s1) : 0; jn[q2] = j < 0 ? 0 : j; }
;             if (more) {
; #pragma unroll
;                 for (int q2 = 0; q2 < 4; ++q2) load_kh8(kq[q2], Ks8 + (size_t)jn[q2] * 4096, h1, lane); }
;             if (__all(jm >= 0 && t - (jm * 64 + 32 * hh + 31) >= 1023)) softmax_half_far(acc, lutg, st, Od);
;             else { bf16x8 pB; softmax_half<1>(acc, (jm < 0 ? 0 : jm) * 64 + 32 * hh, jm >= 0, t, g4, lutg, st, Od, pB); }
;             const long p8 = p_to_fp8(acc);
; #pragma unroll
;             for (int q2 = 0; q2 < 4; ++q2) { const long pm = (qi == q2) ? p8 : 0l; pv_acch8(Od, vq[q2], pm); }
;             if (more) {
; #pragma unroll
;                 for (int q2 = 0; q2 < 4; ++q2) load_vh8(vq[q2], Vs8 + (size_t)jn[q2] * 4096, h1, lane); }
;         }
.Lslb_join:
	v_sub_f32_e32 v24, v144, v213
	v_cvt_pk_fp8_f32 v31, v216, v217
	v_mul_f32_e32 v24, 0x3fb8aa3b, v24
	v_cvt_pk_fp8_f32 v144, v220, v221
	v_exp_f32_e32 v24, v24
	v_cvt_pk_fp8_f32 v31, v218, v219 op_sel:[0,0,1]
	v_cvt_pk_fp8_f32 v144, v222, v223 op_sel:[0,0,1]
	v_mul_f32_e32 v23, v24, v23
	v_mul_f32_e32 v22, v24, v22
	v_mul_f32_e32 v21, v24, v21
	v_mul_f32_e32 v20, v24, v20
	v_cndmask_b32_e64 v27, 0, v144, s[6:7]
	v_cndmask_b32_e64 v26, 0, v31, s[6:7]
	v_mul_f32_e32 v19, v24, v19
	v_mul_f32_e32 v18, v24, v18
	v_mul_f32_e32 v17, v24, v17
	v_mul_f32_e32 v16, v24, v16
	v_mul_f32_e32 v15, v24, v15
	v_mul_f32_e32 v14, v24, v14
	v_mul_f32_e32 v13, v24, v13
	v_mul_f32_e32 v12, v24, v12
	v_mul_f32_e32 v11, v24, v11
	v_mul_f32_e32 v10, v24, v10
	v_mul_f32_e32 v9, v24, v9
	v_mul_f32_e32 v8, v24, v8
	s_waitcnt vmcnt(31)
	s_nop 0
	v_mfma_f32_16x16x32_fp8_fp8 v[20:23], v[134:135], v[26:27], v[20:23]
	v_mfma_f32_16x16x32_fp8_fp8 v[16:19], v[136:137], v[26:27], v[16:19]
	s_waitcnt vmcnt(30)
	v_mfma_f32_16x16x32_fp8_fp8 v[12:15], v[138:139], v[26:27], v[12:15]
	v_mfma_f32_16x16x32_fp8_fp8 v[8:11], v[140:141], v[26:27], v[8:11]
	v_cndmask_b32_e64 v27, 0, v144, s[8:9]
	v_cndmask_b32_e64 v26, 0, v31, s[8:9]
	s_waitcnt vmcnt(29)
	s_nop 0
	v_mfma_f32_16x16x32_fp8_fp8 v[20:23], v[152:153], v[26:27], v[20:23]
	v_mfma_f32_16x16x32_fp8_fp8 v[16:19], v[154:155], v[26:27], v[16:19]
	s_waitcnt vmcnt(28)
	v_mfma_f32_16x16x32_fp8_fp8 v[12:15], v[156:157], v[26:27], v[12:15]
	v_mfma_f32_16x16x32_fp8_fp8 v[8:11], v[158:159], v[26:27], v[8:11]
	v_cndmask_b32_e64 v27, 0, v144, s[10:11]
	v_cndmask_b32_e64 v26, 0, v31, s[10:11]
	s_waitcnt vmcnt(27)
	s_nop 0
	v_mfma_f32_16x16x32_fp8_fp8 v[20:23], v[160:161], v[26:27], v[20:23]
	v_mfma_f32_16x16x32_fp8_fp8 v[16:19], v[162:163], v[26:27], v[16:19]
	s_waitcnt vmcnt(26)
	v_mfma_f32_16x16x32_fp8_fp8 v[12:15], v[246:247], v[26:27], v[12:15]
	v_mfma_f32_16x16x32_fp8_fp8 v[8:11], v[248:249], v[26:27], v[8:11]
	v_cndmask_b32_e64 v27, 0, v144, s[12:13]
	v_cndmask_b32_e64 v26, 0, v31, s[12:13]
	s_waitcnt vmcnt(25)
	s_nop 0
	v_mfma_f32_16x16x32_fp8_fp8 v[20:23], v[0:1], v[26:27], v[20:23]
	v_mfma_f32_16x16x32_fp8_fp8 v[16:19], v[2:3], v[26:27], v[16:19]
	s_waitcnt vmcnt(24)
	v_mfma_f32_16x16x32_fp8_fp8 v[12:15], v[4:5], v[26:27], v[12:15]
	v_mfma_f32_16x16x32_fp8_fp8 v[8:11], v[6:7], v[26:27], v[8:11]
	s_add_u32 s48, s0, s26
	s_addc_u32 s49, s1, s27
	global_load_dwordx4 v[134:137], v229, s[48:49]
	global_load_dwordx4 v[138:141], v229, s[48:49] offset:1024
	s_add_u32 s48, s0, s28
	s_addc_u32 s49, s1, s29
	global_load_dwordx4 v[152:155], v229, s[48:49]
	global_load_dwordx4 v[156:159], v229, s[48:49] offset:1024
	s_add_u32 s48, s0, s30
	s_addc_u32 s49, s1, s31
	global_load_dwordx4 v[160:163], v229, s[48:49]
	global_load_dwordx4 v[246:249], v229, s[48:49] offset:1024
	s_add_u32 s48, s0, s34
	s_addc_u32 s49, s1, s35
	global_load_dwordx4 v[0:3], v229, s[48:49]
	global_load_dwordx4 v[4:7], v229, s[48:49] offset:1024
	v_fmac_f32_e32 v215, v212, v24
	s_add_i32 s24, s24, 32
	s_nop 0
	v_mov_b32_e32 v212, v215
	v_mov_b32_e32 v144, v213
	s_add_i32 s32, s32, 1
	s_mov_b64 s[36:37], s[26:27]
	s_mov_b64 s[38:39], s[28:29]
	s_mov_b64 s[40:41], s[30:31]
	s_mov_b64 s[84:85], s[34:35]
	s_add_i32 s25, s32, 1
	s_cmp_lt_i32 s25, s42
	s_cbranch_scc1 .Lsl_steady

; __device__ __forceinline__ void nsa_wave(CArgs* Ap, int l, int b, int g, int tq0, const LAS float* lut, LAS float* imp, int lane) {
;     ...
;         for (int hs = h0; hs < nh; ++hs) {
;             const int s = hs >> 1, hh = hs & 1;
;             const int jm = __shfl(selreg, 16 * qi + s);
;             f32x4 acc[2];
;             acc[0] = (f32x4){0.f, 0.f, 0.f, 0.f}; acc[1] = (f32x4){0.f, 0.f, 0.f, 0.f};
; #pragma unroll
;             for (int q2 = 0; q2 < 4; ++q2) { long qm[2]; qm[0] = (qi == q2) ? q8[0] : 0l; qm[1] = (qi == q2) ? q8[1] : 0l; qk_acch8(acc, kq[q2], qm); }
;             const bool more = hs + 1 < nh; const int s1 = (hs + 1) >> 1, h1 = (hs + 1) & 1;
;             int jn[4];
; #pragma unroll
;             for (int q2 = 0; q2 < 4; ++q2) { int j = more ? __builtin_amdgcn_readlane(selreg, 16 * q2 + s1) : 0; jn[q2] = j < 0 ? 0 : j; }
;             if (more) {
; #pragma unroll
;                 for (int q2 = 0; q2 < 4; ++q2) load_kh8(kq[q2], Ks8 + (size_t)jn[q2] * 4096, h1, lane); }
;             if (__all(jm >= 0 && t - (jm * 64 + 32 * hh + 31) >= 1023)) softmax_half_far(acc, lutg, st, Od);
;             else { bf16x8 pB; softmax_half<1>(acc, (jm < 0 ? 0 : jm) * 64 + 32 * hh, jm >= 0, t, g4, lutg, st, Od, pB); }
;             const long p8 = p_to_fp8(acc);
; #pragma unroll
;             for (int q2 = 0; q2 < 4; ++q2) { const long pm = (qi == q2) ? p8 : 0l; pv_acch8(Od, vq[q2], pm); }
;             if (more) {
; #pragma unroll
;                 for (int q2 = 0; q2 < 4; ++q2) load_vh8(vq[q2], Vs8 + (size_t)jn[q2] * 4096, h1, lane); }
;         }
.Lslc_join:
	v_sub_f32_e32 v24, v144, v213
	v_cvt_pk_fp8_f32 v31, v216, v217
	v_mul_f32_e32 v24, 0x3fb8aa3b, v24
	v_cvt_pk_fp8_f32 v144, v220, v221
	v_exp_f32_e32 v24, v24
	v_cvt_pk_fp8_f32 v31, v218, v219 op_sel:[0,0,1]
	v_cvt_pk_fp8_f32 v144, v222, v223 op_sel:[0,0,1]
	v_mul_f32_e32 v23, v24, v23
	v_mul_f32_e32 v22, v24, v22
	v_mul_f32_e32 v21, v24, v21
	v_mul_f32_e32 v20, v24, v20
	v_cndmask_b32_e64 v27, 0, v144, s[6:7]
	v_cndmask_b32_e64 v26, 0, v31, s[6:7]
	v_mul_f32_e32 v19, v24, v19
	v_mul_f32_e32 v18, v24, v18
	v_mul_f32_e32 v17, v24, v17
	v_mul_f32_e32 v16, v24, v16
	v_mul_f32_e32 v15, v24, v15
	v_mul_f32_e32 v14, v24, v14
	v_mul_f32_e32 v13, v24, v13
	v_mul_f32_e32 v12, v24, v12
	v_mul_f32_e32 v11, v24, v11
	v_mul_f32_e32 v10, v24, v10
	v_mul_f32_e32 v9, v24, v9
	v_mul_f32_e32 v8, v24, v8
	s_waitcnt vmcnt(23)
	s_nop 0
	v_mfma_f32_16x16x32_fp8_fp8 v[20:23], v[40:41], v[26:27], v[20:23]
	v_mfma_f32_16x16x32_fp8_fp8 v[16:19], v[42:43], v[26:27], v[16:19]
	s_waitcnt vmcnt(22)
	v_mfma_f32_16x16x32_fp8_fp8 v[12:15], v[44:45], v[26:27], v[12:15]
	v_mfma_f32_16x16x32_fp8_fp8 v[8:11], v[46:47], v[26:27], v[8:11]
	v_cndmask_b32_e64 v27, 0, v144, s[8:9]
	v_cndmask_b32_e64 v26, 0, v31, s[8:9]
	s_waitcnt vmcnt(21)
	s_nop 0
	v_mfma_f32_16x16x32_fp8_fp8 v[20:23], v[56:57], v[26:27], v[20:23]
	v_mfma_f32_16x16x32_fp8_fp8 v[16:19], v[58:59], v[26:27], v[16:19]
	s_waitcnt vmcnt(20)
	v_mfma_f32_16x16x32_fp8_fp8 v[12:15], v[60:61], v[26:27], v[12:15]
	v_mfma_f32_16x16x32_fp8_fp8 v[8:11], v[62:63], v[26:27], v[8:11]
	v_cndmask_b32_e64 v27, 0, v144, s[10:11]
	v_cndmask_b32_e64 v26, 0, v31, s[10:11]
	s_waitcnt vmcnt(19)
	s_nop 0
	v_mfma_f32_16x16x32_fp8_fp8 v[20:23], v[74:75], v[26:27], v[20:23]
	v_mfma_f32_16x16x32_fp8_fp8 v[16:19], v[76:77], v[26:27], v[16:19]
	s_waitcnt vmcnt(18)
	v_mfma_f32_16x16x32_fp8_fp8 v[12:15], v[78:79], v[26:27], v[12:15]
	v_mfma_f32_16x16x32_fp8_fp8 v[8:11], v[80:81], v[26:27], v[8:11]
	v_cndmask_b32_e64 v27, 0, v144, s[12:13]
	v_cndmask_b32_e64 v26, 0, v31, s[12:13]
	s_waitcnt vmcnt(17)
	s_nop 0
	v_mfma_f32_16x16x32_fp8_fp8 v[20:23], v[106:107], v[26:27], v[20:23]
	v_mfma_f32_16x16x32_fp8_fp8 v[16:19], v[108:109], v[26:27], v[16:19]
	s_waitcnt vmcnt(16)
	v_mfma_f32_16x16x32_fp8_fp8 v[12:15], v[122:123], v[26:27], v[12:15]
	v_mfma_f32_16x16x32_fp8_fp8 v[8:11], v[124:125], v[26:27], v[8:11]
	v_fmac_f32_e32 v215, v212, v24
	s_add_i32 s24, s24, 32
	s_nop 0
	v_mov_b32_e32 v212, v215
	v_mov_b32_e32 v144, v213
	s_waitcnt vmcnt(15)
	v_mfma_f32_16x16x32_fp8_fp8 v[24:27], v[184:185], v[82:83], 0
	v_mov_b32_e32 v214, v165
	s_nop 0
	s_waitcnt vmcnt(14)
	v_mfma_f32_16x16x32_fp8_fp8 v[28:31], v[188:189], v[82:83], 0
	s_nop 0
	s_nop 0
	v_mfma_f32_16x16x32_fp8_fp8 v[24:27], v[186:187], v[104:105], v[24:27]
	v_mfma_f32_16x16x32_fp8_fp8 v[28:31], v[190:191], v[104:105], v[28:31]
	s_waitcnt vmcnt(13)
	v_mfma_f32_16x16x32_fp8_fp8 v[24:27], v[192:193], v[98:99], v[24:27]
	s_waitcnt vmcnt(12)
	v_mfma_f32_16x16x32_fp8_fp8 v[28:31], v[196:197], v[98:99], v[28:31]
	v_mfma_f32_16x16x32_fp8_fp8 v[24:27], v[194:195], v[110:111], v[24:27]
	v_mfma_f32_16x16x32_fp8_fp8 v[28:31], v[198:199], v[110:111], v[28:31]
	s_waitcnt vmcnt(11)
	v_mfma_f32_16x16x32_fp8_fp8 v[24:27], v[230:231], v[100:101], v[24:27]
	s_waitcnt vmcnt(10)
	v_mfma_f32_16x16x32_fp8_fp8 v[28:31], v[234:235], v[100:101], v[28:31]
	v_mfma_f32_16x16x32_fp8_fp8 v[24:27], v[232:233], v[120:121], v[24:27]
	v_mfma_f32_16x16x32_fp8_fp8 v[28:31], v[236:237], v[120:121], v[28:31]
	s_waitcnt vmcnt(9)
	v_mfma_f32_16x16x32_fp8_fp8 v[24:27], v[238:239], v[102:103], v[24:27]
	s_waitcnt vmcnt(8)
	v_mfma_f32_16x16x32_fp8_fp8 v[28:31], v[242:243], v[102:103], v[28:31]
	v_mfma_f32_16x16x32_fp8_fp8 v[24:27], v[240:241], v[126:127], v[24:27]
	v_mfma_f32_16x16x32_fp8_fp8 v[28:31], v[244:245], v[126:127], v[28:31]

; __device__ __forceinline__ void nsa_wave(CArgs* Ap, int l, int b, int g, int tq0, const LAS float* lut, LAS float* imp, int lane) {
;     ...
;         for (int hs = h0; hs < nh; ++hs) {
;             const int s = hs >> 1, hh = hs & 1;
;             const int jm = __shfl(selreg, 16 * qi + s);
;             f32x4 acc[2];
;             acc[0] = (f32x4){0.f, 0.f, 0.f, 0.f}; acc[1] = (f32x4){0.f, 0.f, 0.f, 0.f};
; #pragma unroll
;             for (int q2 = 0; q2 < 4; ++q2) { long qm[2]; qm[0] = (qi == q2) ? q8[0] : 0l; qm[1] = (qi == q2) ? q8[1] : 0l; qk_acch8(acc, kq[q2], qm); }
;             const bool more = hs + 1 < nh; const int s1 = (hs + 1) >> 1, h1 = (hs + 1) & 1;
;             int jn[4];
; #pragma unroll
;             for (int q2 = 0; q2 < 4; ++q2) { int j = more ? __builtin_amdgcn_readlane(selreg, 16 * q2 + s1) : 0; jn[q2] = j < 0 ? 0 : j; }
;             if (more) {
; #pragma unroll
;                 for (int q2 = 0; q2 < 4; ++q2) load_kh8(kq[q2], Ks8 + (size_t)jn[q2] * 4096, h1, lane); }
;             if (__all(jm >= 0 && t - (jm * 64 + 32 * hh + 31) >= 1023)) softmax_half_far(acc, lutg, st, Od);
;             else { bf16x8 pB; softmax_half<1>(acc, (jm < 0 ? 0 : jm) * 64 + 32 * hh, jm >= 0, t, g4, lutg, st, Od, pB); }
;             const long p8 = p_to_fp8(acc);
; #pragma unroll
;             for (int q2 = 0; q2 < 4; ++q2) { const long pm = (qi == q2) ? p8 : 0l; pv_acch8(Od, vq[q2], pm); }
;             if (more) {
; #pragma unroll
;                 for (int q2 = 0; q2 < 4; ++q2) load_vh8(vq[q2], Vs8 + (size_t)jn[q2] * 4096, h1, lane); }
;         }
;         float lt = st.l; lt += __shfl_xor(lt, 16); lt += __shfl_xor(lt, 32);
.Lsld_join:
	v_sub_f32_e32 v24, v144, v213
	v_cvt_pk_fp8_f32 v31, v216, v217
	v_mul_f32_e32 v24, 0x3fb8aa3b, v24
	v_cvt_pk_fp8_f32 v144, v220, v221
	v_exp_f32_e32 v24, v24
	v_cvt_pk_fp8_f32 v31, v218, v219 op_sel:[0,0,1]
	v_cvt_pk_fp8_f32 v144, v222, v223 op_sel:[0,0,1]
	v_mul_f32_e32 v23, v24, v23
	v_mul_f32_e32 v22, v24, v22
	v_mul_f32_e32 v21, v24, v21
	v_mul_f32_e32 v20, v24, v20
	v_cndmask_b32_e64 v27, 0, v144, s[6:7]
	v_cndmask_b32_e64 v26, 0, v31, s[6:7]
	v_mul_f32_e32 v19, v24, v19
	v_mul_f32_e32 v18, v24, v18
	v_mul_f32_e32 v17, v24, v17
	v_mul_f32_e32 v16, v24, v16
	v_mul_f32_e32 v15, v24, v15
	v_mul_f32_e32 v14, v24, v14
	v_mul_f32_e32 v13, v24, v13
	v_mul_f32_e32 v12, v24, v12
	v_mul_f32_e32 v11, v24, v11
	v_mul_f32_e32 v10, v24, v10
	v_mul_f32_e32 v9, v24, v9
	v_mul_f32_e32 v8, v24, v8
	s_waitcnt vmcnt(7)
	s_nop 0
	v_mfma_f32_16x16x32_fp8_fp8 v[20:23], v[134:135], v[26:27], v[20:23]
	v_mfma_f32_16x16x32_fp8_fp8 v[16:19], v[136:137], v[26:27], v[16:19]
	s_waitcnt vmcnt(6)
	v_mfma_f32_16x16x32_fp8_fp8 v[12:15], v[138:139], v[26:27], v[12:15]
	v_mfma_f32_16x16x32_fp8_fp8 v[8:11], v[140:141], v[26:27], v[8:11]
	v_cndmask_b32_e64 v27, 0, v144, s[8:9]
	v_cndmask_b32_e64 v26, 0, v31, s[8:9]
	s_waitcnt vmcnt(5)
	s_nop 0
	v_mfma_f32_16x16x32_fp8_fp8 v[20:23], v[152:153], v[26:27], v[20:23]
	v_mfma_f32_16x16x32_fp8_fp8 v[16:19], v[154:155], v[26:27], v[16:19]
	s_waitcnt vmcnt(4)
	v_mfma_f32_16x16x32_fp8_fp8 v[12:15], v[156:157], v[26:27], v[12:15]
	v_mfma_f32_16x16x32_fp8_fp8 v[8:11], v[158:159], v[26:27], v[8:11]
	v_cndmask_b32_e64 v27, 0, v144, s[10:11]
	v_cndmask_b32_e64 v26, 0, v31, s[10:11]
	s_waitcnt vmcnt(3)
	s_nop 0
	v_mfma_f32_16x16x32_fp8_fp8 v[20:23], v[160:161], v[26:27], v[20:23]
	v_mfma_f32_16x16x32_fp8_fp8 v[16:19], v[162:163], v[26:27], v[16:19]
	s_waitcnt vmcnt(2)
	v_mfma_f32_16x16x32_fp8_fp8 v[12:15], v[246:247], v[26:27], v[12:15]
	v_mfma_f32_16x16x32_fp8_fp8 v[8:11], v[248:249], v[26:27], v[8:11]
	v_cndmask_b32_e64 v27, 0, v144, s[12:13]
	v_cndmask_b32_e64 v26, 0, v31, s[12:13]
	s_waitcnt vmcnt(1)
	s_nop 0
	v_mfma_f32_16x16x32_fp8_fp8 v[20:23], v[0:1], v[26:27], v[20:23]
	v_mfma_f32_16x16x32_fp8_fp8 v[16:19], v[2:3], v[26:27], v[16:19]
	s_waitcnt vmcnt(0)
	v_mfma_f32_16x16x32_fp8_fp8 v[12:15], v[4:5], v[26:27], v[12:15]
	v_mfma_f32_16x16x32_fp8_fp8 v[8:11], v[6:7], v[26:27], v[8:11]
	v_fmac_f32_e32 v215, v212, v24
	s_add_i32 s24, s24, 32
	s_nop 0
	v_mov_b32_e32 v212, v215
	v_mov_b32_e32 v144, v213
	s_nop 7
	ds_read_b128 v[0:3], v93 offset:4096
	ds_read_b128 v[4:7], v93 offset:5120
	s_branch .LBB0_1280

; __device__ __forceinline__ unsigned pk2(float lo, float hi) { return pg8::cvt_pk_bf16(lo, hi); }
; __device__ __forceinline__ float fexp(float x) { return __expf(x); }
; template <int MODE>
; __device__ __forceinline__ void softmax_block(f32x4 (&acc)[4], int base, bool ok, int t, int g4, const LAS float* lutg, SmState& st, f32x4 (&O)[4], bf16x8 (&pB)[2]) {
;     ...
;     const float mn = fmaxf(st.m, mx);
;     const float sc = fexp(st.m - mn);
;     float ls = 0.f;
; #pragma unroll
;     for (int nt = 0; nt < 4; ++nt)
; #pragma unroll
;         for (int i = 0; i < 4; ++i) { const float p = ((vm >> (nt * 4 + i)) & 1u) ? fexp(acc[nt][i] - mn) : 0.f; acc[nt][i] = p; ls += p; }
;     st.l = st.l * sc + ls; st.m = mn;
; #pragma unroll
;     for (int dt = 0; dt < 4; ++dt) O[dt] = O[dt] * sc;
; #pragma unroll
;     for (int hh = 0; hh < 2; ++hh) { u32x4 w; w.x = pk2(acc[2 * hh][0], acc[2 * hh][1]); w.y = pk2(acc[2 * hh][2], acc[2 * hh][3]); w.z = pk2(acc[2 * hh + 1][0], acc[2 * hh + 1][1]); w.w = pk2(acc[2 * hh + 1][2], acc[2 * hh + 1][3]);
;         pB[hh] = __builtin_bit_cast(bf16x8, w); }
; __device__ __forceinline__ void nsa_wave(CArgs* Ap, int l, int b, int g, int tq0, const LAS float* lut, LAS float* imp, int lane) {
;     ...
;         for (int jb = jb0; jb <= jb1; ++jb) {
;             bf16x8 kf[4][2]; load_k(kf, Kw + (size_t)jb * 4096, lane);
;             bf16x8 vf[4][2]; load_v(vf, VWT + (size_t)jb * 4096, lane);
;             f32x4 acc[4];
; #pragma unroll
;             for (int nt = 0; nt < 4; ++nt) acc[nt] = (f32x4){0.f, 0.f, 0.f, 0.f};
;             qk_acc(acc, kf, qB);
;             bf16x8 pB[2];
;             softmax_block<2>(acc, jb * 64, true, t, g4, lutg, st, Od, pB);
;             pv_acc(Od, vf, pB);
;         }
.Lwin_sm_done:
	v_mul_f32_e32 v39, v150, v39
	v_mul_f32_e32 v38, v150, v38
	v_mul_f32_e32 v37, v150, v37
	v_mul_f32_e32 v36, v150, v36
	v_mul_f32_e32 v35, v150, v35
	v_mul_f32_e32 v34, v150, v34
	v_mul_f32_e32 v33, v150, v33
	v_mul_f32_e32 v32, v150, v32
	v_mul_f32_e32 v31, v150, v31
	v_mul_f32_e32 v30, v150, v30
	v_mul_f32_e32 v29, v150, v29
	v_mul_f32_e32 v28, v150, v28
	v_mul_f32_e32 v27, v150, v27
	v_mul_f32_e32 v26, v150, v26
	v_mul_f32_e32 v25, v150, v25
	v_mul_f32_e32 v24, v150, v24
	v_add_f32_e32 v127, v229, v228
	v_add_f32_e32 v127, v230, v127
	v_add_f32_e32 v127, v231, v127
	v_add_f32_e32 v127, v232, v127
	v_add_f32_e32 v127, v233, v127
	v_add_f32_e32 v127, v234, v127
	v_add_f32_e32 v127, v235, v127
	v_add_f32_e32 v127, v236, v127
	v_add_f32_e32 v127, v237, v127
	v_add_f32_e32 v127, v238, v127
	v_add_f32_e32 v127, v239, v127
	v_add_f32_e32 v127, v240, v127
	v_add_f32_e32 v127, v241, v127
	v_add_f32_e32 v127, v242, v127
	v_add_f32_e32 v127, v243, v127
	v_fmac_f32_e32 v127, v126, v150
	v_cvt_pk_bf16_f32 v244, v228, v229
	v_cvt_pk_bf16_f32 v245, v230, v231
	v_cvt_pk_bf16_f32 v246, v232, v233
	v_cvt_pk_bf16_f32 v247, v234, v235
	v_cvt_pk_bf16_f32 v248, v236, v237
	v_cvt_pk_bf16_f32 v249, v238, v239
	v_cvt_pk_bf16_f32 v250, v240, v241
	v_cvt_pk_bf16_f32 v251, v242, v243
	v_mov_b32_e32 v126, v127
	s_cmp_lt_i32 s0, s21
	s_cbranch_scc0 .Lwin_last
	s_waitcnt vmcnt(8)
	v_mfma_f32_16x16x32_bf16 v[36:39], v[72:75], v[244:247], v[36:39]
	v_mfma_f32_16x16x32_bf16 v[32:35], v[80:83], v[244:247], v[32:35]
	v_mfma_f32_16x16x32_bf16 v[28:31], v[108:111], v[244:247], v[28:31]
	v_mfma_f32_16x16x32_bf16 v[24:27], v[116:119], v[244:247], v[24:27]
	v_mfma_f32_16x16x32_bf16 v[36:39], v[76:79], v[248:251], v[36:39]
	v_mfma_f32_16x16x32_bf16 v[32:35], v[104:107], v[248:251], v[32:35]
	v_mfma_f32_16x16x32_bf16 v[28:31], v[112:115], v[248:251], v[28:31]
	v_mfma_f32_16x16x32_bf16 v[24:27], v[120:123], v[248:251], v[24:27]
	global_load_dwordx4 v[72:75], v[124:125], off offset:-4096
	global_load_dwordx4 v[76:79], v[124:125], off offset:-3072
	global_load_dwordx4 v[80:83], v[124:125], off offset:-2048
	global_load_dwordx4 v[104:107], v[124:125], off offset:-1024
	global_load_dwordx4 v[108:111], v[124:125], off offset:0
	global_load_dwordx4 v[112:115], v[124:125], off offset:1024
	global_load_dwordx4 v[116:119], v[124:125], off offset:2048
	global_load_dwordx4 v[120:123], v[124:125], off offset:3072
	s_branch .Lwin_loop
